# attention phase: one static s_setprio 1 for waves 4-7 (younger-half priority lever), cleared after the loop
# baseline (speedup 1.0000x reference)
; __device__ __forceinline__ void attn_unit(int b, int qb, int kvh, const bf16_t* __restrict__ QP, const bf16_t* __restrict__ KP, const bf16_t* __restrict__ VT, const float* sink, bf16_t* MIX, unsigned char* ldsb, int tid, int wave, int lane) {
;     const int fr = lane & 15, fq = lane >> 4, hq = kvh * 4 + (wave >> 1), q0 = qb * 64 + (wave & 1) * 32;
; __global__ void __launch_bounds__(512, 2) fwd_megakernel(Args args) {
;     ...
;     { const Ctx X = mkctx(lds); for (int u = X.bx; u < 1024; u += X.G) attn_unit(u >> 7, (u >> 1) & 63, u & 1, QP, KP, VT, args.in[13], MIX, lds, X.tid, X.wave, X.lane); }
.Lat_adv_11:
	v_readfirstlane_b32 s0, v206
	s_nop 3
	s_lshr_b32 s0, s0, 6
	s_cmp_ge_u32 s0, 4
	s_cbranch_scc0 .Lat_prio_done
	s_setprio 1

; __global__ void __launch_bounds__(512, 2) fwd_megakernel(Args args) {
;     ...
;     { const Ctx X = mkctx(lds); for (int u = X.bx; u < 1024; u += X.G) attn_unit(u >> 7, (u >> 1) & 63, u & 1, QP, KP, VT, args.in[13], MIX, lds, X.tid, X.wave, X.lane); }
.Lat_cont:
	s_cmp_lt_u32 s27, s26
	s_cbranch_scc1 .Lat_loop
	s_setprio 0
	s_add_u32 s6, s88, 0x1a600000
	s_addc_u32 s7, s89, 0
